# P12 epilogue: second-half conv weight/bias loads prefetched at the top of the epilogue into free VGPRs (one load round trip per tile removed)
# baseline (speedup 1.0000x reference)
.Lmy_prio_skip5:
.LBB0_914:
	ds_read_b128 v[128:131], v187
	ds_read_b128 v[132:135], v187 offset:1024
	ds_read_b128 v[136:139], v187 offset:2048
	ds_read_b128 v[140:143], v187 offset:3072
	ds_read_b128 v[144:147], v188
	ds_read_b128 v[148:151], v188 offset:1024
	ds_read_b128 v[152:155], v188 offset:2048
	ds_read_b128 v[156:159], v188 offset:3072
	s_add_u32 s52, s50, 0x100
	s_addc_u32 s53, s51, 0
	s_cmp_eq_u32 s96, 60
	s_cselect_b32 s57, s41, s53
	s_cselect_b32 s56, s47, s52
	s_cselect_b32 s55, s39, s49
	s_cselect_b32 s54, s34, s35
	s_add_i32 m0, s67, 0xc000
	ds_read_b128 v[178:181], v189
	ds_read_b128 v[192:195], v189 offset:1024
	ds_read_b128 v[196:199], v189 offset:2048
	ds_read_b128 v[200:203], v189 offset:3072
	ds_read_b128 v[204:207], v189 offset:4096
	ds_read_b128 v[208:211], v189 offset:5120
	ds_read_b128 v[212:215], v189 offset:6144
	ds_read_b128 v[216:219], v189 offset:7168
	global_load_lds_dwordx4 v170, s[50:51]
	s_add_i32 m0, s67, 0xe000
	s_nop 0
	global_load_lds_dwordx4 v172, s[50:51]
	s_waitcnt vmcnt(8)
	s_waitcnt lgkmcnt(0)
	s_barrier
	s_waitcnt lgkmcnt(0)
	v_mfma_f32_16x16x32_bf16 v[124:127], v[128:131], v[178:181], v[124:127]
	v_mfma_f32_16x16x32_bf16 v[60:63], v[136:139], v[178:181], v[60:63]
	v_mfma_f32_16x16x32_bf16 v[116:119], v[128:131], v[196:199], v[116:119]
	v_mfma_f32_16x16x32_bf16 v[56:59], v[136:139], v[196:199], v[56:59]
	v_mfma_f32_16x16x32_bf16 v[108:111], v[128:131], v[204:207], v[108:111]
	v_mfma_f32_16x16x32_bf16 v[44:47], v[136:139], v[204:207], v[44:47]
	v_mfma_f32_16x16x32_bf16 v[104:107], v[128:131], v[212:215], v[104:107]
	v_mfma_f32_16x16x32_bf16 v[40:43], v[136:139], v[212:215], v[40:43]
	v_mfma_f32_16x16x32_bf16 v[124:127], v[132:135], v[192:195], v[124:127]
	v_mfma_f32_16x16x32_bf16 v[60:63], v[140:143], v[192:195], v[60:63]
	v_mfma_f32_16x16x32_bf16 v[116:119], v[132:135], v[200:203], v[116:119]
	v_mfma_f32_16x16x32_bf16 v[56:59], v[140:143], v[200:203], v[56:59]
	v_mfma_f32_16x16x32_bf16 v[108:111], v[132:135], v[208:211], v[108:111]
	v_mfma_f32_16x16x32_bf16 v[44:47], v[140:143], v[208:211], v[44:47]
	v_mfma_f32_16x16x32_bf16 v[104:107], v[132:135], v[216:219], v[104:107]
	v_mfma_f32_16x16x32_bf16 v[40:43], v[140:143], v[216:219], v[40:43]
	v_mfma_f32_16x16x32_bf16 v[120:123], v[144:147], v[178:181], v[120:123]
	v_mfma_f32_16x16x32_bf16 v[52:55], v[152:155], v[178:181], v[52:55]
	v_mfma_f32_16x16x32_bf16 v[112:115], v[144:147], v[196:199], v[112:115]
	v_mfma_f32_16x16x32_bf16 v[48:51], v[152:155], v[196:199], v[48:51]
	v_mfma_f32_16x16x32_bf16 v[100:103], v[144:147], v[204:207], v[100:103]
	v_mfma_f32_16x16x32_bf16 v[36:39], v[152:155], v[204:207], v[36:39]
	v_mfma_f32_16x16x32_bf16 v[96:99], v[144:147], v[212:215], v[96:99]
	v_mfma_f32_16x16x32_bf16 v[32:35], v[152:155], v[212:215], v[32:35]
	v_mfma_f32_16x16x32_bf16 v[120:123], v[148:151], v[192:195], v[120:123]
	v_mfma_f32_16x16x32_bf16 v[52:55], v[156:159], v[192:195], v[52:55]
	v_mfma_f32_16x16x32_bf16 v[112:115], v[148:151], v[200:203], v[112:115]
	v_mfma_f32_16x16x32_bf16 v[48:51], v[156:159], v[200:203], v[48:51]
	v_mfma_f32_16x16x32_bf16 v[100:103], v[148:151], v[208:211], v[100:103]
	v_mfma_f32_16x16x32_bf16 v[36:39], v[156:159], v[208:211], v[36:39]
	v_mfma_f32_16x16x32_bf16 v[96:99], v[148:151], v[216:219], v[96:99]
	v_mfma_f32_16x16x32_bf16 v[32:35], v[156:159], v[216:219], v[32:35]
	s_barrier
	s_add_i32 s50, s92, s66
	s_mov_b32 m0, s50
	ds_read_b128 v[178:181], v189 offset:16384
	ds_read_b128 v[192:195], v189 offset:17408
	ds_read_b128 v[196:199], v189 offset:18432
	ds_read_b128 v[200:203], v189 offset:19456
	ds_read_b128 v[204:207], v189 offset:20480
	ds_read_b128 v[208:211], v189 offset:21504
	ds_read_b128 v[212:215], v189 offset:22528
	ds_read_b128 v[216:219], v189 offset:23552
	global_load_lds_dwordx4 v164, s[54:55]
	s_add_i32 m0, s50, 0x2000
	s_add_u32 s50, s54, 0x100000
	v_lshl_add_u64 v[182:183], s[54:55], 0, v[168:169]
	s_addc_u32 s51, s55, 0
	s_add_i32 s97, s93, s66
	global_load_lds_dwordx4 v168, s[54:55]
	s_mov_b32 m0, s97
	global_load_lds_dwordx4 v164, s[50:51]
	s_add_i32 m0, s97, 0x2000
	s_nop 0
	global_load_lds_dwordx4 v168, s[50:51]
	s_mov_b32 m0, s67
	s_nop 0
	global_load_lds_dwordx4 v162, s[56:57]
	s_mov_b32 m0, s68
	s_nop 0
	global_load_lds_dwordx4 v166, s[56:57]
	s_waitcnt vmcnt(8)
	s_waitcnt lgkmcnt(0)
	s_barrier
	s_waitcnt lgkmcnt(0)
	v_mfma_f32_16x16x32_bf16 v[92:95], v[128:131], v[178:181], v[92:95]
	v_mfma_f32_16x16x32_bf16 v[28:31], v[136:139], v[178:181], v[28:31]
	v_mfma_f32_16x16x32_bf16 v[84:87], v[128:131], v[196:199], v[84:87]
	v_mfma_f32_16x16x32_bf16 v[24:27], v[136:139], v[196:199], v[24:27]
	v_mfma_f32_16x16x32_bf16 v[76:79], v[128:131], v[204:207], v[76:79]
	v_mfma_f32_16x16x32_bf16 v[12:15], v[136:139], v[204:207], v[12:15]
	v_mfma_f32_16x16x32_bf16 v[72:75], v[128:131], v[212:215], v[72:75]
	v_mfma_f32_16x16x32_bf16 v[8:11], v[136:139], v[212:215], v[8:11]
	v_mfma_f32_16x16x32_bf16 v[92:95], v[132:135], v[192:195], v[92:95]
	v_mfma_f32_16x16x32_bf16 v[28:31], v[140:143], v[192:195], v[28:31]
	v_mfma_f32_16x16x32_bf16 v[84:87], v[132:135], v[200:203], v[84:87]
	v_mfma_f32_16x16x32_bf16 v[24:27], v[140:143], v[200:203], v[24:27]
	v_mfma_f32_16x16x32_bf16 v[76:79], v[132:135], v[208:211], v[76:79]
	v_mfma_f32_16x16x32_bf16 v[12:15], v[140:143], v[208:211], v[12:15]
	v_mfma_f32_16x16x32_bf16 v[72:75], v[132:135], v[216:219], v[72:75]
	v_mfma_f32_16x16x32_bf16 v[8:11], v[140:143], v[216:219], v[8:11]
	v_mfma_f32_16x16x32_bf16 v[88:91], v[144:147], v[178:181], v[88:91]
	v_mfma_f32_16x16x32_bf16 v[20:23], v[152:155], v[178:181], v[20:23]
	v_mfma_f32_16x16x32_bf16 v[80:83], v[144:147], v[196:199], v[80:83]
	v_mfma_f32_16x16x32_bf16 v[16:19], v[152:155], v[196:199], v[16:19]
	v_mfma_f32_16x16x32_bf16 v[68:71], v[144:147], v[204:207], v[68:71]
	v_mfma_f32_16x16x32_bf16 v[4:7], v[152:155], v[204:207], v[4:7]
	v_mfma_f32_16x16x32_bf16 v[64:67], v[144:147], v[212:215], v[64:67]
	v_mfma_f32_16x16x32_bf16 v[0:3], v[152:155], v[212:215], v[0:3]
	v_mfma_f32_16x16x32_bf16 v[88:91], v[148:151], v[192:195], v[88:91]
	v_mfma_f32_16x16x32_bf16 v[20:23], v[156:159], v[192:195], v[20:23]
	v_mfma_f32_16x16x32_bf16 v[80:83], v[148:151], v[200:203], v[80:83]
	v_mfma_f32_16x16x32_bf16 v[16:19], v[156:159], v[200:203], v[16:19]
	v_mfma_f32_16x16x32_bf16 v[68:71], v[148:151], v[208:211], v[68:71]
	v_mfma_f32_16x16x32_bf16 v[4:7], v[156:159], v[208:211], v[4:7]
	v_mfma_f32_16x16x32_bf16 v[64:67], v[148:151], v[216:219], v[64:67]
	v_mfma_f32_16x16x32_bf16 v[0:3], v[156:159], v[216:219], v[0:3]
	s_barrier
	s_add_i32 s97, 0, 0x18000
	s_add_i32 vcc_lo, 0, 0x1c000
	v_add_u32_e32 v140, s97, v184
	v_add_u32_e32 v156, vcc_lo, v184
	ds_read_b128 v[128:131], v140
	ds_read_b128 v[132:135], v140 offset:1024
	ds_read_b128 v[136:139], v140 offset:2048
	ds_read_b128 v[140:143], v140 offset:3072
	ds_read_b128 v[144:147], v156
	ds_read_b128 v[148:151], v156 offset:1024
	ds_read_b128 v[152:155], v156 offset:2048
	ds_read_b128 v[156:159], v156 offset:3072
	s_add_u32 s50, s56, 0x100000
	s_addc_u32 s51, s57, 0
	s_mov_b32 m0, s69
	ds_read_b128 v[178:181], v189 offset:32768
	ds_read_b128 v[192:195], v189 offset:33792
	ds_read_b128 v[196:199], v189 offset:34816
	ds_read_b128 v[200:203], v189 offset:35840
	ds_read_b128 v[204:207], v189 offset:36864
	ds_read_b128 v[208:211], v189 offset:37888
	ds_read_b128 v[212:215], v189 offset:38912
	ds_read_b128 v[216:219], v189 offset:39936
	global_load_lds_dwordx4 v162, s[50:51]
	s_mov_b32 m0, s76
	s_nop 0
	global_load_lds_dwordx4 v166, s[50:51]
	s_waitcnt vmcnt(8)
	s_waitcnt lgkmcnt(0)
	s_barrier
	s_waitcnt lgkmcnt(0)
	v_mfma_f32_16x16x32_bf16 v[124:127], v[128:131], v[178:181], v[124:127]
	v_mfma_f32_16x16x32_bf16 v[60:63], v[136:139], v[178:181], v[60:63]
	v_mfma_f32_16x16x32_bf16 v[116:119], v[128:131], v[196:199], v[116:119]
	v_mfma_f32_16x16x32_bf16 v[56:59], v[136:139], v[196:199], v[56:59]
	v_mfma_f32_16x16x32_bf16 v[108:111], v[128:131], v[204:207], v[108:111]
	v_mfma_f32_16x16x32_bf16 v[44:47], v[136:139], v[204:207], v[44:47]
	v_mfma_f32_16x16x32_bf16 v[104:107], v[128:131], v[212:215], v[104:107]
	v_mfma_f32_16x16x32_bf16 v[40:43], v[136:139], v[212:215], v[40:43]
	v_mfma_f32_16x16x32_bf16 v[124:127], v[132:135], v[192:195], v[124:127]
	v_mfma_f32_16x16x32_bf16 v[60:63], v[140:143], v[192:195], v[60:63]
	v_mfma_f32_16x16x32_bf16 v[116:119], v[132:135], v[200:203], v[116:119]
	v_mfma_f32_16x16x32_bf16 v[56:59], v[140:143], v[200:203], v[56:59]
	v_mfma_f32_16x16x32_bf16 v[108:111], v[132:135], v[208:211], v[108:111]
	v_mfma_f32_16x16x32_bf16 v[44:47], v[140:143], v[208:211], v[44:47]
	v_mfma_f32_16x16x32_bf16 v[104:107], v[132:135], v[216:219], v[104:107]
	v_mfma_f32_16x16x32_bf16 v[40:43], v[140:143], v[216:219], v[40:43]
	v_mfma_f32_16x16x32_bf16 v[120:123], v[144:147], v[178:181], v[120:123]
	v_mfma_f32_16x16x32_bf16 v[52:55], v[152:155], v[178:181], v[52:55]
	v_mfma_f32_16x16x32_bf16 v[112:115], v[144:147], v[196:199], v[112:115]
	v_mfma_f32_16x16x32_bf16 v[48:51], v[152:155], v[196:199], v[48:51]
	v_mfma_f32_16x16x32_bf16 v[100:103], v[144:147], v[204:207], v[100:103]
	v_mfma_f32_16x16x32_bf16 v[36:39], v[152:155], v[204:207], v[36:39]
	v_mfma_f32_16x16x32_bf16 v[96:99], v[144:147], v[212:215], v[96:99]
	v_mfma_f32_16x16x32_bf16 v[32:35], v[152:155], v[212:215], v[32:35]
	v_mfma_f32_16x16x32_bf16 v[120:123], v[148:151], v[192:195], v[120:123]
	v_mfma_f32_16x16x32_bf16 v[52:55], v[156:159], v[192:195], v[52:55]
	v_mfma_f32_16x16x32_bf16 v[112:115], v[148:151], v[200:203], v[112:115]
	v_mfma_f32_16x16x32_bf16 v[48:51], v[156:159], v[200:203], v[48:51]
	v_mfma_f32_16x16x32_bf16 v[100:103], v[148:151], v[208:211], v[100:103]
	v_mfma_f32_16x16x32_bf16 v[36:39], v[156:159], v[208:211], v[36:39]
	v_mfma_f32_16x16x32_bf16 v[96:99], v[148:151], v[216:219], v[96:99]
	v_mfma_f32_16x16x32_bf16 v[32:35], v[156:159], v[216:219], v[32:35]
	s_barrier
	s_add_i32 s50, s97, s66
	s_mov_b32 m0, s50
	ds_read_b128 v[178:181], v189 offset:49152
	ds_read_b128 v[192:195], v189 offset:50176
	ds_read_b128 v[196:199], v189 offset:51200
	ds_read_b128 v[200:203], v189 offset:52224
	ds_read_b128 v[204:207], v189 offset:53248
	ds_read_b128 v[208:211], v189 offset:54272
	ds_read_b128 v[212:215], v189 offset:55296
	ds_read_b128 v[216:219], v189 offset:56320
	s_add_u32 s100, s54, 0x80
	s_addc_u32 s101, s55, 0
	global_load_lds_dwordx4 v164, s[100:101]
	s_add_i32 m0, s50, 0x2000
	s_add_u32 s50, s54, 0x100080
	v_lshl_add_u64 v[160:161], v[182:183], 0, s[10:11]
	s_addc_u32 s51, s55, 0
	s_add_i32 s54, vcc_lo, s66
	global_load_lds_dwordx4 v[160:161], off
	s_mov_b32 m0, s54
	s_nop 0
	global_load_lds_dwordx4 v164, s[50:51]
	s_add_i32 m0, s54, 0x2000
	s_nop 0
	global_load_lds_dwordx4 v168, s[50:51]
	s_mov_b32 m0, s84
	s_nop 0
	s_add_u32 s100, s56, 0x80
	s_addc_u32 s101, s57, 0
	global_load_lds_dwordx4 v162, s[100:101]
	s_mov_b32 m0, s85
	s_nop 0
	s_add_u32 s100, s56, 0x80
	s_addc_u32 s101, s57, 0
	global_load_lds_dwordx4 v166, s[100:101]
	s_add_i32 s96, s96, 2
	s_add_u32 s35, s35, 0x100
	s_addc_u32 s49, s49, 0
	s_cmp_gt_u32 s96, 61
	s_waitcnt vmcnt(8)
	s_waitcnt lgkmcnt(0)
	s_barrier
	s_waitcnt lgkmcnt(0)
	v_mfma_f32_16x16x32_bf16 v[92:95], v[128:131], v[178:181], v[92:95]
	v_mfma_f32_16x16x32_bf16 v[28:31], v[136:139], v[178:181], v[28:31]
	v_mfma_f32_16x16x32_bf16 v[84:87], v[128:131], v[196:199], v[84:87]
	v_mfma_f32_16x16x32_bf16 v[24:27], v[136:139], v[196:199], v[24:27]
	v_mfma_f32_16x16x32_bf16 v[76:79], v[128:131], v[204:207], v[76:79]
	v_mfma_f32_16x16x32_bf16 v[12:15], v[136:139], v[204:207], v[12:15]
	v_mfma_f32_16x16x32_bf16 v[72:75], v[128:131], v[212:215], v[72:75]
	v_mfma_f32_16x16x32_bf16 v[8:11], v[136:139], v[212:215], v[8:11]
	v_mfma_f32_16x16x32_bf16 v[92:95], v[132:135], v[192:195], v[92:95]
	v_mfma_f32_16x16x32_bf16 v[28:31], v[140:143], v[192:195], v[28:31]
	v_mfma_f32_16x16x32_bf16 v[84:87], v[132:135], v[200:203], v[84:87]
	v_mfma_f32_16x16x32_bf16 v[24:27], v[140:143], v[200:203], v[24:27]
	v_mfma_f32_16x16x32_bf16 v[76:79], v[132:135], v[208:211], v[76:79]
	v_mfma_f32_16x16x32_bf16 v[12:15], v[140:143], v[208:211], v[12:15]
	v_mfma_f32_16x16x32_bf16 v[72:75], v[132:135], v[216:219], v[72:75]
	v_mfma_f32_16x16x32_bf16 v[8:11], v[140:143], v[216:219], v[8:11]
	v_mfma_f32_16x16x32_bf16 v[88:91], v[144:147], v[178:181], v[88:91]
	v_mfma_f32_16x16x32_bf16 v[20:23], v[152:155], v[178:181], v[20:23]
	v_mfma_f32_16x16x32_bf16 v[80:83], v[144:147], v[196:199], v[80:83]
	v_mfma_f32_16x16x32_bf16 v[16:19], v[152:155], v[196:199], v[16:19]
	v_mfma_f32_16x16x32_bf16 v[68:71], v[144:147], v[204:207], v[68:71]
	v_mfma_f32_16x16x32_bf16 v[4:7], v[152:155], v[204:207], v[4:7]
	v_mfma_f32_16x16x32_bf16 v[64:67], v[144:147], v[212:215], v[64:67]
	v_mfma_f32_16x16x32_bf16 v[0:3], v[152:155], v[212:215], v[0:3]
	v_mfma_f32_16x16x32_bf16 v[88:91], v[148:151], v[192:195], v[88:91]
	v_mfma_f32_16x16x32_bf16 v[20:23], v[156:159], v[192:195], v[20:23]
	v_mfma_f32_16x16x32_bf16 v[80:83], v[148:151], v[200:203], v[80:83]
	v_mfma_f32_16x16x32_bf16 v[16:19], v[156:159], v[200:203], v[16:19]
	v_mfma_f32_16x16x32_bf16 v[68:71], v[148:151], v[208:211], v[68:71]
	v_mfma_f32_16x16x32_bf16 v[4:7], v[156:159], v[208:211], v[4:7]
	v_mfma_f32_16x16x32_bf16 v[64:67], v[148:151], v[216:219], v[64:67]
	v_mfma_f32_16x16x32_bf16 v[0:3], v[156:159], v[216:219], v[0:3]
	s_barrier
	s_mov_b64 s[50:51], s[52:53]
	s_cbranch_scc0 .LBB0_914
	s_setprio 0
	s_lshl_b32 s34, s46, 2
	v_lshl_or_b32 v178, s48, 7, v186
	s_add_i32 s34, s34, s65
	v_ashrrev_i32_e32 v179, 31, v178
	s_mul_hi_i32 s35, s34, 0x30000
	s_mul_i32 s39, s34, 0x30000
	v_readlane_b32 s24, v254, 31
	v_readlane_b32 s25, v254, 32
	v_readlane_b32 s26, v254, 33
	v_readlane_b32 s27, v254, 34
	v_lshl_add_u64 v[220:221], v[178:179], 2, s[88:89]
	global_load_dwordx4 v[220:223], v[220:221], off offset:16
	v_lshl_add_u64 v[242:243], v[178:179], 2, s[94:95]
	global_load_dwordx4 v[242:245], v[242:243], off offset:16
	v_lshl_add_u64 v[246:247], v[178:179], 2, s[36:37]
	global_load_dwordx4 v[246:249], v[246:247], off offset:16
	v_lshl_add_u64 v[250:251], v[178:179], 2, s[62:63]
	global_load_dwordx4 v[250:253], v[250:251], off offset:16
	v_lshl_add_u64 v[226:227], v[178:179], 2, s[24:25]
	global_load_dwordx4 v[226:229], v[226:227], off offset:16
	v_lshl_add_u64 v[230:231], v[178:179], 2, s[58:59]
	global_load_dwordx4 v[230:233], v[230:231], off offset:16
	v_lshl_add_u64 v[234:235], v[178:179], 2, s[26:27]
	global_load_dwordx4 v[234:237], v[234:235], off offset:16
	v_lshl_add_u64 v[238:239], v[178:179], 2, s[60:61]
	global_load_dwordx4 v[238:241], v[238:239], off offset:16
	s_and_saveexec_b64 s[48:49], s[0:1]
	s_cbranch_execz .LBB0_917
	s_add_u32 s50, s79, s39
	s_addc_u32 s51, s81, s35
	v_lshl_add_u64 v[132:133], v[178:179], 1, s[50:51]
	v_add_co_u32_e32 v134, vcc, s78, v132
	s_nop 2
	v_cvt_pk_bf16_f32 v128, v124, v125
	s_nop 2
	v_cvt_pk_bf16_f32 v129, v126, v127
	s_nop 2
	v_cvt_pk_bf16_f32 v130, v60, v61
	s_nop 2
	v_cvt_pk_bf16_f32 v131, v62, v63
	s_nop 1
	v_addc_co_u32_e32 v135, vcc, 0, v133, vcc
	s_mov_b32 s17, 0xc000
	global_store_dwordx4 v[132:133], v[128:131], off
	s_nop 1
	s_nop 2
	v_cvt_pk_bf16_f32 v128, v120, v121
	s_nop 2
	v_cvt_pk_bf16_f32 v129, v122, v123
	s_nop 2
	v_cvt_pk_bf16_f32 v130, v52, v53
	s_nop 2
	v_cvt_pk_bf16_f32 v131, v54, v55
	global_store_dwordx4 v[134:135], v[128:131], off
	v_add_co_u32_e32 v134, vcc, s17, v132
	s_nop 0
	s_nop 2
	v_cvt_pk_bf16_f32 v128, v116, v117
	s_nop 2
	v_cvt_pk_bf16_f32 v129, v118, v119
	s_nop 2
	v_cvt_pk_bf16_f32 v130, v56, v57
	s_nop 2
	v_cvt_pk_bf16_f32 v131, v58, v59
	s_nop 0
	v_addc_co_u32_e32 v135, vcc, 0, v133, vcc
	v_add_co_u32_e32 v132, vcc, 0x12000, v132
	global_store_dwordx4 v[134:135], v[128:131], off
	s_nop 0
	v_addc_co_u32_e32 v133, vcc, 0, v133, vcc
	s_nop 2
	v_cvt_pk_bf16_f32 v128, v112, v113
	s_nop 2
	v_cvt_pk_bf16_f32 v129, v114, v115
	s_nop 2
	v_cvt_pk_bf16_f32 v130, v48, v49
	s_nop 2
	v_cvt_pk_bf16_f32 v131, v50, v51
	global_store_dwordx4 v[132:133], v[128:131], off

.LBB0_923:
	s_or_b64 exec, exec, s[48:49]
	v_readlane_b32 s16, v254, 23
	v_lshlrev_b64 v[144:145], 2, v[178:179]
	v_readlane_b32 s24, v254, 31
	v_readlane_b32 s25, v254, 32
	v_readlane_b32 s26, v254, 33
	v_readlane_b32 s27, v254, 34
	v_lshl_add_u64 v[180:181], s[24:25], 0, v[144:145]
	v_lshl_add_u64 v[136:137], s[88:89], 0, v[144:145]
	global_load_dwordx4 v[128:131], v[180:181], off
	global_load_dwordx4 v[150:153], v[136:137], off
	v_lshl_add_u64 v[182:183], s[26:27], 0, v[144:145]
	v_lshl_add_u64 v[136:137], s[36:37], 0, v[144:145]
	global_load_dwordx4 v[132:135], v[182:183], off
	v_lshl_add_u64 v[140:141], s[58:59], 0, v[144:145]
	global_load_dwordx4 v[136:139], v[136:137], off
	v_lshl_add_u64 v[146:147], s[94:95], 0, v[144:145]
	global_load_dwordx4 v[140:143], v[140:141], off
	s_nop 0
	global_load_dwordx4 v[154:157], v[146:147], off
	v_lshl_add_u64 v[146:147], s[60:61], 0, v[144:145]
	v_lshl_add_u64 v[148:149], s[62:63], 0, v[144:145]
	global_load_dwordx4 v[144:147], v[146:147], off
	s_nop 0
	global_load_dwordx4 v[158:161], v[148:149], off
	v_mov_b32_dpp v194, v97 row_ror:1 row_mask:0xf bank_mask:0xf bound_ctrl:1
	v_mov_b32_dpp v193, v96 row_ror:1 row_mask:0xf bank_mask:0xf bound_ctrl:1
	v_mov_b32_dpp v148, v104 row_ror:1 row_mask:0xf bank_mask:0xf bound_ctrl:1
	v_mov_b32_dpp v197, v124 row_ror:15 row_mask:0xf bank_mask:0xf bound_ctrl:1
	v_mov_b32_dpp v201, v120 row_ror:15 row_mask:0xf bank_mask:0xf bound_ctrl:1
	v_mov_b32_dpp v149, v105 row_ror:1 row_mask:0xf bank_mask:0xf bound_ctrl:1
	v_mov_b32_dpp v202, v121 row_ror:15 row_mask:0xf bank_mask:0xf bound_ctrl:1
	v_mov_b32_dpp v195, v98 row_ror:1 row_mask:0xf bank_mask:0xf bound_ctrl:1
	v_mov_b32_dpp v196, v99 row_ror:1 row_mask:0xf bank_mask:0xf bound_ctrl:1
	v_mov_b32_dpp v203, v122 row_ror:15 row_mask:0xf bank_mask:0xf bound_ctrl:1
	v_mov_b32_dpp v198, v125 row_ror:15 row_mask:0xf bank_mask:0xf bound_ctrl:1
	v_mov_b32_dpp v204, v123 row_ror:15 row_mask:0xf bank_mask:0xf bound_ctrl:1
	v_mov_b32_dpp v191, v106 row_ror:1 row_mask:0xf bank_mask:0xf bound_ctrl:1
	v_mov_b32_dpp v199, v126 row_ror:15 row_mask:0xf bank_mask:0xf bound_ctrl:1
	v_mov_b32_dpp v192, v107 row_ror:1 row_mask:0xf bank_mask:0xf bound_ctrl:1
	v_mov_b32_dpp v200, v127 row_ror:15 row_mask:0xf bank_mask:0xf bound_ctrl:1
	v_readlane_b32 s17, v254, 24
	v_readlane_b32 s18, v254, 25
	v_readlane_b32 s19, v254, 26
	v_readlane_b32 s20, v254, 27
	v_readlane_b32 s21, v254, 28
	v_readlane_b32 s22, v254, 29
	v_readlane_b32 s23, v254, 30
	v_readlane_b32 s28, v254, 35
	v_readlane_b32 s29, v254, 36
	v_readlane_b32 s30, v254, 37
	v_readlane_b32 s31, v254, 38
	s_waitcnt vmcnt(0)
	v_fma_f32 v148, v128, v148, v132
	v_fma_f32 v205, v124, v128, v132
	v_fma_f32 v194, v151, v194, v137
	v_fma_f32 v193, v150, v193, v136
	v_fmac_f32_e32 v194, v121, v155
	v_fmac_f32_e32 v193, v120, v154
	v_fmac_f32_e32 v148, v124, v140
	v_fmac_f32_e32 v194, v113, v159
	v_fmac_f32_e32 v193, v112, v158
	v_mul_f32_e32 v124, v194, v194
	v_fma_f32 v206, v120, v150, v136
	v_mul_f32_e32 v120, v193, v193
	v_fmamk_f32 v124, v124, 0xbdd2d3e7, v190
	v_fmamk_f32 v120, v120, 0xbdd2d3e7, v190
	v_mul_f32_e32 v124, v194, v124
	v_mul_f32_e32 v120, v193, v120
	v_exp_f32_e32 v124, v124
	v_exp_f32_e32 v120, v120
	v_fma_f32 v149, v129, v149, v133
	v_fmac_f32_e32 v149, v125, v141
	v_add_f32_e32 v124, 1.0, v124
	v_add_f32_e32 v120, 1.0, v120
	v_rcp_f32_e32 v124, v124
	v_rcp_f32_e32 v120, v120
	v_fma_f32 v121, v121, v151, v137
	v_fmac_f32_e32 v149, v117, v145
	v_mul_f32_e32 v124, v194, v124
	v_fmac_f32_e32 v121, v113, v155
	v_fmac_f32_e32 v148, v116, v144
	v_mul_f32_e32 v120, v193, v120
	v_mul_f32_e32 v124, v149, v124
	v_fmac_f32_e32 v121, v101, v159
	v_mul_f32_e32 v120, v148, v120
	v_cvt_pk_bf16_f32 v148, v120, v124
	v_mul_f32_e32 v124, v121, v121
	v_fmamk_f32 v124, v124, 0xbdd2d3e7, v190
	v_mul_f32_e32 v124, v121, v124
	v_exp_f32_e32 v124, v124
	v_fma_f32 v195, v152, v195, v138
	v_fmac_f32_e32 v195, v122, v156
	v_fma_f32 v122, v122, v152, v138
	v_add_f32_e32 v124, 1.0, v124
	v_rcp_f32_e32 v124, v124
	v_fma_f32 v196, v153, v196, v139
	v_fmac_f32_e32 v206, v112, v154
	v_fmac_f32_e32 v122, v114, v156
	v_fmac_f32_e32 v196, v123, v157
	v_fmac_f32_e32 v195, v114, v160
	v_fmac_f32_e32 v206, v100, v158
	v_fmac_f32_e32 v122, v102, v160
	v_fmac_f32_e32 v196, v115, v161
	v_mul_f32_e32 v207, v195, v195
	v_mul_f32_e32 v209, v206, v206
	v_mul_f32_e32 v121, v121, v124
	v_mul_f32_e32 v124, v122, v122
	v_mul_f32_e32 v208, v196, v196
	v_fmamk_f32 v207, v207, 0xbdd2d3e7, v190
	v_fmamk_f32 v209, v209, 0xbdd2d3e7, v190
	v_fmamk_f32 v124, v124, 0xbdd2d3e7, v190
	v_fmamk_f32 v208, v208, 0xbdd2d3e7, v190
	v_mul_f32_e32 v207, v195, v207
	v_mul_f32_e32 v209, v206, v209
	v_fma_f32 v125, v125, v129, v133
	v_mul_f32_e32 v124, v122, v124
	v_fma_f32 v123, v123, v153, v139
	v_mul_f32_e32 v208, v196, v208
	v_exp_f32_e32 v207, v207
	v_exp_f32_e32 v209, v209
	v_fmac_f32_e32 v125, v117, v141
	v_exp_f32_e32 v124, v124
	v_fmac_f32_e32 v123, v115, v157
	v_fma_f32 v191, v130, v191, v134
	v_exp_f32_e32 v208, v208
	v_fmac_f32_e32 v125, v109, v145
	v_fmac_f32_e32 v123, v103, v161
	v_fmac_f32_e32 v191, v126, v142
	v_mul_f32_e32 v121, v125, v121
	v_fma_f32 v125, v126, v130, v134
	v_mul_f32_e32 v126, v123, v123
	v_fmamk_f32 v126, v126, 0xbdd2d3e7, v190
	v_add_f32_e32 v207, 1.0, v207
	v_add_f32_e32 v120, 1.0, v209
	v_add_f32_e32 v124, 1.0, v124
	v_mul_f32_e32 v126, v123, v126
	v_add_f32_e32 v208, 1.0, v208
	v_rcp_f32_e32 v207, v207
	v_rcp_f32_e32 v120, v120
	v_rcp_f32_e32 v124, v124
	v_exp_f32_e32 v126, v126
	v_rcp_f32_e32 v208, v208
	v_fma_f32 v113, v113, v151, v137
	v_fma_f32 v192, v131, v192, v135
	v_fmac_f32_e32 v205, v116, v140
	v_fma_f32 v112, v112, v150, v136
	v_fmac_f32_e32 v113, v101, v155
	v_fma_f32 v101, v101, v151, v137
	v_fmac_f32_e32 v192, v127, v143
	v_fmac_f32_e32 v191, v118, v146
	v_mul_f32_e32 v193, v195, v207
	v_fmac_f32_e32 v205, v108, v144
	v_mul_f32_e32 v120, v206, v120
	v_mul_f32_e32 v122, v122, v124
	v_add_f32_e32 v124, 1.0, v126
	v_fmac_f32_e32 v112, v100, v154
	v_fmac_f32_e32 v101, v97, v155
	v_fmac_f32_e32 v192, v119, v147
	v_mul_f32_e32 v194, v196, v208
	v_mul_f32_e32 v149, v191, v193
	v_mul_f32_e32 v120, v205, v120
	v_rcp_f32_e32 v124, v124
	v_fmac_f32_e32 v112, v96, v158
	v_fmac_f32_e32 v101, v159, v202
	v_mul_f32_e32 v191, v192, v194
	v_cvt_pk_bf16_f32 v149, v149, v191
	v_fmac_f32_e32 v125, v118, v142
	v_cvt_pk_bf16_f32 v120, v120, v121
	v_mul_f32_e32 v121, v112, v112
	v_fmac_f32_e32 v113, v97, v159
	v_mul_f32_e32 v97, v101, v101
	v_fmac_f32_e32 v125, v110, v146
	v_fmamk_f32 v121, v121, 0xbdd2d3e7, v190
	v_fmamk_f32 v97, v97, 0xbdd2d3e7, v190
	v_mul_f32_e32 v122, v125, v122
	v_fma_f32 v125, v127, v131, v135
	v_mul_f32_e32 v121, v112, v121
	v_mul_f32_e32 v97, v101, v97
	v_fmac_f32_e32 v125, v119, v143
	v_mul_f32_e32 v123, v123, v124
	v_exp_f32_e32 v124, v121
	v_exp_f32_e32 v97, v97
	v_fmac_f32_e32 v125, v111, v147
	v_mul_f32_e32 v123, v125, v123
	v_cvt_pk_bf16_f32 v121, v122, v123
	v_mul_f32_e32 v123, v113, v113
	v_add_f32_e32 v122, 1.0, v124
	v_fmamk_f32 v123, v123, 0xbdd2d3e7, v190
	v_fma_f32 v100, v100, v150, v136
	v_add_f32_e32 v97, 1.0, v97
	v_rcp_f32_e32 v122, v122
	v_mul_f32_e32 v123, v113, v123
	v_fmac_f32_e32 v100, v96, v154
	v_rcp_f32_e32 v97, v97
	v_exp_f32_e32 v123, v123
	v_fmac_f32_e32 v100, v158, v201
	v_fma_f32 v116, v116, v128, v132
	v_mul_f32_e32 v96, v100, v100
	v_fmac_f32_e32 v116, v108, v140
	v_fmamk_f32 v96, v96, 0xbdd2d3e7, v190
	v_fmac_f32_e32 v116, v104, v144
	v_mul_f32_e32 v112, v112, v122
	v_mul_f32_e32 v96, v100, v96
	v_mul_f32_e32 v97, v101, v97
	v_fma_f32 v101, v102, v152, v138
	v_mul_f32_e32 v112, v116, v112
	v_add_f32_e32 v116, 1.0, v123
	v_fma_f32 v114, v114, v152, v138
	v_exp_f32_e32 v96, v96
	v_fmac_f32_e32 v101, v98, v156
	v_rcp_f32_e32 v116, v116
	v_fmac_f32_e32 v114, v102, v156
	v_fmac_f32_e32 v101, v160, v203
	v_fmac_f32_e32 v114, v98, v160
	v_mul_f32_e32 v98, v101, v101
	v_fmamk_f32 v98, v98, 0xbdd2d3e7, v190
	v_add_f32_e32 v96, 1.0, v96
	v_mul_f32_e32 v98, v101, v98
	v_mul_f32_e32 v113, v113, v116
	v_mul_f32_e32 v116, v114, v114
	v_rcp_f32_e32 v96, v96
	v_exp_f32_e32 v98, v98
	v_fma_f32 v102, v103, v153, v139
	v_fmamk_f32 v116, v116, 0xbdd2d3e7, v190
	v_fma_f32 v115, v115, v153, v139
	v_fmac_f32_e32 v102, v99, v157
	v_fma_f32 v117, v117, v129, v133
	v_mul_f32_e32 v116, v114, v116
	v_fmac_f32_e32 v115, v103, v157
	v_fmac_f32_e32 v102, v161, v204
	v_fmac_f32_e32 v117, v109, v141
	v_exp_f32_e32 v116, v116
	v_fmac_f32_e32 v115, v99, v161
	v_mul_f32_e32 v99, v102, v102
	v_fmac_f32_e32 v117, v105, v145
	v_mul_f32_e32 v96, v100, v96
	v_fma_f32 v100, v109, v129, v133
	v_add_f32_e32 v98, 1.0, v98
	v_fmamk_f32 v99, v99, 0xbdd2d3e7, v190
	v_mul_f32_e32 v113, v117, v113
	v_fma_f32 v117, v118, v130, v134
	v_mul_f32_e32 v118, v115, v115
	v_fmac_f32_e32 v100, v105, v141
	v_rcp_f32_e32 v98, v98
	v_mul_f32_e32 v99, v102, v99
	v_fmamk_f32 v118, v118, 0xbdd2d3e7, v190
	v_fmac_f32_e32 v100, v145, v198
	v_exp_f32_e32 v99, v99
	v_add_f32_e32 v116, 1.0, v116
	v_mul_f32_e32 v118, v115, v118
	v_mul_f32_e32 v97, v100, v97
	v_fma_f32 v100, v110, v130, v134
	v_rcp_f32_e32 v116, v116
	v_exp_f32_e32 v118, v118
	v_fmac_f32_e32 v100, v106, v142
	v_fmac_f32_e32 v100, v146, v199
	v_mul_f32_e32 v98, v101, v98
	v_mul_f32_e32 v100, v100, v98
	v_add_f32_e32 v98, 1.0, v99
	v_rcp_f32_e32 v98, v98
	v_mul_f32_e32 v114, v114, v116
	v_add_f32_e32 v116, 1.0, v118
	v_fmac_f32_e32 v117, v110, v142
	v_rcp_f32_e32 v116, v116
	v_fmac_f32_e32 v117, v106, v146
	v_mul_f32_e32 v114, v117, v114
	v_fma_f32 v117, v119, v131, v135
	v_mul_f32_e32 v98, v102, v98
	v_mov_b32_dpp v102, v64 row_ror:1 row_mask:0xf bank_mask:0xf bound_ctrl:1
	v_fmac_f32_e32 v117, v111, v143
	v_fma_f32 v102, v150, v102, v136
	v_fmac_f32_e32 v117, v107, v147
	v_mul_f32_e32 v115, v115, v116
	v_fmac_f32_e32 v102, v88, v154
	v_mul_f32_e32 v115, v117, v115
	v_fmac_f32_e32 v102, v80, v158
	v_cvt_pk_bf16_f32 v112, v112, v113
	v_cvt_pk_bf16_f32 v113, v114, v115
	v_mul_f32_e32 v115, v102, v102
	v_fmamk_f32 v115, v115, 0xbdd2d3e7, v190
	v_mov_b32_dpp v103, v65 row_ror:1 row_mask:0xf bank_mask:0xf bound_ctrl:1
	v_mul_f32_e32 v115, v102, v115
	v_exp_f32_e32 v115, v115
	v_fma_f32 v103, v151, v103, v137
	v_fmac_f32_e32 v103, v89, v155
	v_fma_f32 v108, v108, v128, v132
	v_fmac_f32_e32 v103, v81, v159
	v_fmac_f32_e32 v108, v104, v140
	v_fma_f32 v99, v111, v131, v135
	v_mul_f32_e32 v117, v103, v103
	v_fmac_f32_e32 v108, v144, v197
	v_fmac_f32_e32 v99, v107, v143
	v_add_f32_e32 v115, 1.0, v115
	v_fmamk_f32 v117, v117, 0xbdd2d3e7, v190
	v_mul_f32_e32 v96, v108, v96
	v_fmac_f32_e32 v99, v147, v200
	v_rcp_f32_e32 v115, v115
	v_mul_f32_e32 v117, v103, v117
	v_mul_f32_e32 v99, v99, v98
	v_cvt_pk_bf16_f32 v98, v96, v97
	v_mov_b32_dpp v96, v72 row_ror:1 row_mask:0xf bank_mask:0xf bound_ctrl:1
	v_exp_f32_e32 v117, v117
	v_fma_f32 v96, v128, v96, v132
	v_fmac_f32_e32 v96, v92, v140
	v_fmac_f32_e32 v96, v84, v144
	v_mul_f32_e32 v102, v102, v115
	v_mul_f32_e32 v96, v96, v102
	v_add_f32_e32 v102, 1.0, v117
	v_rcp_f32_e32 v102, v102
	v_mov_b32_dpp v104, v66 row_ror:1 row_mask:0xf bank_mask:0xf bound_ctrl:1
	v_mov_b32_dpp v97, v73 row_ror:1 row_mask:0xf bank_mask:0xf bound_ctrl:1
	v_fma_f32 v97, v129, v97, v133
	v_mul_f32_e32 v102, v103, v102
	v_fma_f32 v103, v152, v104, v138
	v_fmac_f32_e32 v103, v90, v156
	v_fmac_f32_e32 v103, v82, v160
	v_mul_f32_e32 v104, v103, v103
	v_fmamk_f32 v104, v104, 0xbdd2d3e7, v190
	v_mul_f32_e32 v104, v103, v104
	v_exp_f32_e32 v104, v104
	v_fmac_f32_e32 v97, v93, v141
	v_mov_b32_dpp v105, v67 row_ror:1 row_mask:0xf bank_mask:0xf bound_ctrl:1
	v_fmac_f32_e32 v97, v85, v145
	v_mul_f32_e32 v97, v97, v102
	v_add_f32_e32 v102, 1.0, v104
	v_fma_f32 v104, v153, v105, v139
	v_fmac_f32_e32 v104, v91, v157
	v_fmac_f32_e32 v104, v83, v161
	v_mul_f32_e32 v105, v104, v104
	v_fmamk_f32 v105, v105, 0xbdd2d3e7, v190
	v_rcp_f32_e32 v102, v102
	v_mul_f32_e32 v105, v104, v105
	v_cvt_pk_bf16_f32 v99, v100, v99
	v_mov_b32_dpp v100, v74 row_ror:1 row_mask:0xf bank_mask:0xf bound_ctrl:1
	v_exp_f32_e32 v105, v105
	v_fma_f32 v100, v130, v100, v134
	v_fmac_f32_e32 v100, v94, v142
	v_fmac_f32_e32 v100, v86, v146
	v_mul_f32_e32 v102, v103, v102
	v_mov_b32_dpp v110, v88 row_ror:15 row_mask:0xf bank_mask:0xf bound_ctrl:1
	v_mul_f32_e32 v100, v100, v102
	v_add_f32_e32 v102, 1.0, v105
	v_fma_f32 v88, v88, v150, v136
	v_rcp_f32_e32 v102, v102
	v_fmac_f32_e32 v88, v80, v154
	v_mov_b32_dpp v101, v75 row_ror:1 row_mask:0xf bank_mask:0xf bound_ctrl:1
	v_fmac_f32_e32 v88, v68, v158
	v_fma_f32 v101, v131, v101, v135
	v_cvt_pk_bf16_f32 v96, v96, v97
	v_mul_f32_e32 v97, v88, v88
	v_fmac_f32_e32 v101, v95, v143
	v_fmamk_f32 v97, v97, 0xbdd2d3e7, v190
	v_fmac_f32_e32 v101, v87, v147
	v_mul_f32_e32 v102, v104, v102
	v_mul_f32_e32 v97, v88, v97
	v_mov_b32_dpp v111, v89 row_ror:15 row_mask:0xf bank_mask:0xf bound_ctrl:1
	v_mul_f32_e32 v101, v101, v102
	v_exp_f32_e32 v102, v97
	v_fma_f32 v89, v89, v151, v137
	v_fmac_f32_e32 v89, v81, v155
	v_fmac_f32_e32 v89, v69, v159
	v_cvt_pk_bf16_f32 v97, v100, v101
	v_mul_f32_e32 v101, v89, v89
	v_add_f32_e32 v100, 1.0, v102
	v_fmamk_f32 v101, v101, 0xbdd2d3e7, v190
	v_rcp_f32_e32 v100, v100
	v_mul_f32_e32 v101, v89, v101
	v_exp_f32_e32 v101, v101
	v_mov_b32_dpp v106, v92 row_ror:15 row_mask:0xf bank_mask:0xf bound_ctrl:1
	v_fma_f32 v92, v92, v128, v132
	v_fmac_f32_e32 v92, v84, v140
	v_fmac_f32_e32 v92, v76, v144
	v_mul_f32_e32 v88, v88, v100
	v_mul_f32_e32 v88, v92, v88
	v_add_f32_e32 v92, 1.0, v101
	v_rcp_f32_e32 v92, v92
	v_mov_b32_dpp v114, v90 row_ror:15 row_mask:0xf bank_mask:0xf bound_ctrl:1
	v_fma_f32 v90, v90, v152, v138
	v_fmac_f32_e32 v90, v82, v156
	v_fmac_f32_e32 v90, v70, v160
	v_mul_f32_e32 v89, v89, v92
	v_mul_f32_e32 v92, v90, v90
	v_fmamk_f32 v92, v92, 0xbdd2d3e7, v190
	v_mov_b32_dpp v107, v93 row_ror:15 row_mask:0xf bank_mask:0xf bound_ctrl:1
	v_mov_b32_dpp v116, v91 row_ror:15 row_mask:0xf bank_mask:0xf bound_ctrl:1
	v_fma_f32 v93, v93, v129, v133
	v_mul_f32_e32 v92, v90, v92
	v_fma_f32 v91, v91, v153, v139
	v_fmac_f32_e32 v93, v85, v141
	v_exp_f32_e32 v92, v92
	v_fmac_f32_e32 v91, v83, v157
	v_fmac_f32_e32 v93, v77, v145
	v_fmac_f32_e32 v91, v71, v161
	v_mov_b32_dpp v108, v94 row_ror:15 row_mask:0xf bank_mask:0xf bound_ctrl:1
	v_mul_f32_e32 v89, v93, v89
	v_fma_f32 v93, v94, v130, v134
	v_mul_f32_e32 v94, v91, v91
	v_fmamk_f32 v94, v94, 0xbdd2d3e7, v190
	v_add_f32_e32 v92, 1.0, v92
	v_mul_f32_e32 v94, v91, v94
	v_rcp_f32_e32 v92, v92
	v_exp_f32_e32 v94, v94
	v_fma_f32 v80, v80, v150, v136
	v_fmac_f32_e32 v80, v68, v154
	v_mul_f32_e32 v90, v90, v92
	v_add_f32_e32 v92, 1.0, v94
	v_rcp_f32_e32 v92, v92
	v_fmac_f32_e32 v80, v64, v158
	v_fmac_f32_e32 v93, v86, v142
	v_cvt_pk_bf16_f32 v88, v88, v89
	v_mul_f32_e32 v89, v80, v80
	v_fmac_f32_e32 v93, v78, v146
	v_fmamk_f32 v89, v89, 0xbdd2d3e7, v190
	v_mul_f32_e32 v90, v93, v90
	v_fma_f32 v93, v95, v131, v135
	v_mul_f32_e32 v89, v80, v89
	v_fmac_f32_e32 v93, v87, v143
	v_mul_f32_e32 v91, v91, v92
	v_exp_f32_e32 v92, v89
	v_fma_f32 v81, v81, v151, v137
	v_fmac_f32_e32 v93, v79, v147
	v_fmac_f32_e32 v81, v69, v155
	v_fma_f32 v69, v69, v151, v137
	v_mul_f32_e32 v91, v93, v91
	v_fmac_f32_e32 v81, v65, v159
	v_fmac_f32_e32 v69, v65, v155
	v_cvt_pk_bf16_f32 v89, v90, v91
	v_mul_f32_e32 v91, v81, v81
	v_fmac_f32_e32 v69, v159, v111
	v_add_f32_e32 v90, 1.0, v92
	v_fmamk_f32 v91, v91, 0xbdd2d3e7, v190
	v_mul_f32_e32 v65, v69, v69
	v_rcp_f32_e32 v90, v90
	v_mul_f32_e32 v91, v81, v91
	v_fmamk_f32 v65, v65, 0xbdd2d3e7, v190
	v_exp_f32_e32 v91, v91
	v_mul_f32_e32 v65, v69, v65
	v_fma_f32 v84, v84, v128, v132
	v_exp_f32_e32 v65, v65
	v_fmac_f32_e32 v84, v76, v140
	v_fmac_f32_e32 v84, v72, v144
	v_mul_f32_e32 v80, v80, v90
	v_mul_f32_e32 v80, v84, v80
	v_add_f32_e32 v84, 1.0, v91
	v_rcp_f32_e32 v84, v84
	v_fma_f32 v68, v68, v150, v136
	v_add_f32_e32 v65, 1.0, v65
	v_fma_f32 v82, v82, v152, v138
	v_fmac_f32_e32 v68, v64, v154
	v_rcp_f32_e32 v65, v65
	v_fmac_f32_e32 v82, v70, v156
	v_fmac_f32_e32 v68, v158, v110
	v_fmac_f32_e32 v82, v66, v160
	v_mul_f32_e32 v64, v68, v68
	v_mul_f32_e32 v81, v81, v84
	v_mul_f32_e32 v84, v82, v82
	v_fmamk_f32 v64, v64, 0xbdd2d3e7, v190
	v_fmamk_f32 v84, v84, 0xbdd2d3e7, v190
	v_mul_f32_e32 v64, v68, v64
	v_mul_f32_e32 v65, v69, v65
	v_fma_f32 v69, v70, v152, v138
	v_fma_f32 v85, v85, v129, v133
	v_mul_f32_e32 v84, v82, v84
	v_fma_f32 v83, v83, v153, v139
	v_exp_f32_e32 v64, v64
	v_fmac_f32_e32 v69, v66, v156
	v_fmac_f32_e32 v139, v71, v153
	v_fmac_f32_e32 v85, v77, v141
	v_exp_f32_e32 v84, v84
	v_fmac_f32_e32 v83, v71, v157
	v_fmac_f32_e32 v69, v160, v114
	v_fmac_f32_e32 v139, v67, v157
	v_fmac_f32_e32 v85, v73, v145
	v_fmac_f32_e32 v83, v67, v161
	v_mul_f32_e32 v66, v69, v69
	v_fmac_f32_e32 v139, v161, v116
	v_mul_f32_e32 v81, v85, v81
	v_fma_f32 v85, v86, v130, v134
	v_mul_f32_e32 v86, v83, v83
	v_fmamk_f32 v66, v66, 0xbdd2d3e7, v190
	v_mul_f32_e32 v67, v139, v139
	v_fmamk_f32 v86, v86, 0xbdd2d3e7, v190
	v_add_f32_e32 v64, 1.0, v64
	v_mul_f32_e32 v66, v69, v66
	v_fmamk_f32 v67, v67, 0xbdd2d3e7, v190
	v_add_f32_e32 v84, 1.0, v84
	v_mul_f32_e32 v86, v83, v86
	v_rcp_f32_e32 v64, v64
	v_exp_f32_e32 v66, v66
	v_mul_f32_e32 v67, v139, v67
	v_rcp_f32_e32 v84, v84
	v_exp_f32_e32 v86, v86
	v_exp_f32_e32 v67, v67
	v_mul_f32_e32 v64, v68, v64
	v_fma_f32 v68, v77, v129, v133
	v_add_f32_e32 v66, 1.0, v66
	v_mul_f32_e32 v82, v82, v84
	v_add_f32_e32 v84, 1.0, v86
	v_fmac_f32_e32 v68, v73, v141
	v_rcp_f32_e32 v66, v66
	v_add_f32_e32 v67, 1.0, v67
	v_fmac_f32_e32 v85, v78, v142
	v_rcp_f32_e32 v84, v84
	v_fmac_f32_e32 v68, v145, v107
	v_rcp_f32_e32 v67, v67
	v_fmac_f32_e32 v85, v74, v146
	v_fma_f32 v76, v76, v128, v132
	v_mul_f32_e32 v65, v68, v65
	v_fma_f32 v68, v78, v130, v134
	v_mul_f32_e32 v82, v85, v82
	v_fma_f32 v85, v87, v131, v135
	v_fmac_f32_e32 v76, v72, v140
	v_fmac_f32_e32 v68, v74, v142
	v_fmac_f32_e32 v135, v79, v131
	v_mov_b32_dpp v109, v95 row_ror:15 row_mask:0xf bank_mask:0xf bound_ctrl:1
	v_fmac_f32_e32 v85, v79, v143
	v_fmac_f32_e32 v76, v144, v106
	v_fmac_f32_e32 v68, v146, v108
	v_mul_f32_e32 v66, v69, v66
	v_fmac_f32_e32 v135, v75, v143
	v_fmac_f32_e32 v85, v75, v147
	v_mul_f32_e32 v83, v83, v84
	v_mul_f32_e32 v64, v76, v64
	v_mul_f32_e32 v66, v68, v66
	v_fmac_f32_e32 v135, v147, v109
	v_mul_f32_e32 v67, v139, v67
	v_mul_f32_e32 v83, v85, v83
	v_cvt_pk_bf16_f32 v80, v80, v81
	v_cvt_pk_bf16_f32 v81, v82, v83
	v_mul_f32_e32 v67, v135, v67
	v_cvt_pk_bf16_f32 v64, v64, v65
	v_cvt_pk_bf16_f32 v65, v66, v67
	v_or_b32_e32 v66, 4, v178
	v_ashrrev_i32_e32 v67, 31, v66
	v_lshlrev_b64 v[78:79], 2, v[66:67]
	v_lshl_add_u64 v[66:67], s[88:89], 0, v[78:79]
	v_lshl_add_u64 v[68:69], s[94:95], 0, v[78:79]
	v_mov_b64_e32 v[106:107], v[220:221]
	v_mov_b64_e32 v[108:109], v[222:223]
	v_mov_b64_e32 v[102:103], v[242:243]
	v_mov_b64_e32 v[104:105], v[244:245]
	v_lshl_add_u64 v[66:67], s[36:37], 0, v[78:79]
	v_mov_b64_e32 v[66:67], v[246:247]
	v_mov_b64_e32 v[68:69], v[248:249]
	v_lshl_add_u64 v[70:71], s[62:63], 0, v[78:79]
	v_mov_b64_e32 v[116:117], v[250:251]
	v_mov_b64_e32 v[118:119], v[252:253]
	v_mov_b64_e32 v[74:75], v[226:227]
	v_mov_b64_e32 v[76:77], v[228:229]
	v_lshl_add_u64 v[82:83], s[58:59], 0, v[78:79]
	v_mov_b64_e32 v[70:71], v[234:235]
	v_mov_b64_e32 v[72:73], v[236:237]
	v_mov_b64_e32 v[84:85], v[230:231]
	v_mov_b64_e32 v[86:87], v[232:233]
	v_lshl_add_u64 v[78:79], s[60:61], 0, v[78:79]
	v_mov_b64_e32 v[92:93], v[238:239]
	v_mov_b64_e32 v[94:95], v[240:241]
	v_mov_b32_dpp v100, v32 row_ror:1 row_mask:0xf bank_mask:0xf bound_ctrl:1
	v_mov_b32_dpp v110, v33 row_ror:1 row_mask:0xf bank_mask:0xf bound_ctrl:1
	v_mov_b32_dpp v78, v40 row_ror:1 row_mask:0xf bank_mask:0xf bound_ctrl:1
	v_mov_b32_dpp v111, v34 row_ror:1 row_mask:0xf bank_mask:0xf bound_ctrl:1
	v_mov_b32_dpp v79, v41 row_ror:1 row_mask:0xf bank_mask:0xf bound_ctrl:1
	v_mov_b32_dpp v114, v35 row_ror:1 row_mask:0xf bank_mask:0xf bound_ctrl:1
	v_mov_b32_dpp v82, v42 row_ror:1 row_mask:0xf bank_mask:0xf bound_ctrl:1
	v_mov_b32_dpp v83, v43 row_ror:1 row_mask:0xf bank_mask:0xf bound_ctrl:1
	v_lshl_add_u32 v140, s46, 8, v185
	v_mov_b32_dpp v142, v60 row_ror:15 row_mask:0xf bank_mask:0xf bound_ctrl:1
	v_mov_b32_dpp v141, v61 row_ror:15 row_mask:0xf bank_mask:0xf bound_ctrl:1
	v_mov_b32_dpp v91, v62 row_ror:15 row_mask:0xf bank_mask:0xf bound_ctrl:1
	v_mov_b32_dpp v90, v63 row_ror:15 row_mask:0xf bank_mask:0xf bound_ctrl:1
	v_mov_b32_dpp v144, v52 row_ror:15 row_mask:0xf bank_mask:0xf bound_ctrl:1
	v_mov_b32_dpp v143, v53 row_ror:15 row_mask:0xf bank_mask:0xf bound_ctrl:1
	v_mov_b32_dpp v101, v54 row_ror:15 row_mask:0xf bank_mask:0xf bound_ctrl:1
	v_fma_f32 v115, v106, v100, v66
	v_fmac_f32_e32 v115, v52, v102
	v_fmac_f32_e32 v115, v48, v116
	v_mul_f32_e32 v100, v115, v115
	v_fmamk_f32 v100, v100, 0xbdd2d3e7, v190
	v_mul_f32_e32 v100, v115, v100
	v_exp_f32_e32 v122, v100
	v_fma_f32 v110, v107, v110, v67
	v_fmac_f32_e32 v110, v53, v103
	v_fmac_f32_e32 v110, v49, v117
	v_mul_f32_e32 v123, v110, v110
	v_add_f32_e32 v122, 1.0, v122
	v_fmamk_f32 v123, v123, 0xbdd2d3e7, v190
	v_rcp_f32_e32 v122, v122
	v_mul_f32_e32 v123, v110, v123
	v_exp_f32_e32 v123, v123
	v_fma_f32 v78, v74, v78, v70
	v_fmac_f32_e32 v78, v60, v84
	v_fmac_f32_e32 v78, v56, v92
	v_mul_f32_e32 v115, v115, v122
	v_mul_f32_e32 v78, v78, v115
	v_add_f32_e32 v115, 1.0, v123
	v_rcp_f32_e32 v115, v115
	v_fma_f32 v111, v108, v111, v68
	v_fmac_f32_e32 v111, v54, v104
	v_fmac_f32_e32 v111, v50, v118
	v_mul_f32_e32 v110, v110, v115
	v_mul_f32_e32 v115, v111, v111
	v_fmamk_f32 v115, v115, 0xbdd2d3e7, v190
	v_mul_f32_e32 v115, v111, v115
	v_exp_f32_e32 v115, v115
	v_fma_f32 v79, v75, v79, v71
	v_fma_f32 v114, v109, v114, v69
	v_fmac_f32_e32 v79, v61, v85
	v_fmac_f32_e32 v114, v55, v105
	v_fmac_f32_e32 v79, v57, v93
	v_fmac_f32_e32 v114, v51, v119
	v_mul_f32_e32 v79, v79, v110
	v_add_f32_e32 v110, 1.0, v115
	v_mul_f32_e32 v115, v114, v114
	v_fmamk_f32 v115, v115, 0xbdd2d3e7, v190
	v_rcp_f32_e32 v110, v110
	v_mul_f32_e32 v115, v114, v115
	v_exp_f32_e32 v115, v115
	v_fma_f32 v82, v76, v82, v72
	v_fmac_f32_e32 v82, v62, v86
	v_fmac_f32_e32 v82, v58, v94
	v_mul_f32_e32 v110, v111, v110
	v_mul_f32_e32 v82, v82, v110
	v_add_f32_e32 v110, 1.0, v115
	v_rcp_f32_e32 v110, v110
	v_fma_f32 v83, v77, v83, v73
	v_fmac_f32_e32 v83, v63, v87
	v_mov_b32_dpp v100, v55 row_ror:15 row_mask:0xf bank_mask:0xf bound_ctrl:1
	v_fmac_f32_e32 v83, v59, v95
	v_mul_f32_e32 v110, v114, v110
	v_mul_f32_e32 v83, v83, v110
	v_cvt_pk_bf16_f32 v150, v78, v79
	v_cvt_pk_bf16_f32 v151, v82, v83
	s_and_saveexec_b64 s[46:47], s[2:3]
	s_cbranch_execz .LBB0_925
	v_mov_b64_e32 v[78:79], s[12:13]
	v_mad_i64_i32 v[78:79], s[34:35], v140, s78, v[78:79]
	v_lshl_add_u64 v[78:79], v[178:179], 1, v[78:79]
	global_store_dwordx4 v[78:79], v[148:151], off
